# prep loop: k-rows and V row loads issued with the q-row loads; state units remapped XCD-local; earlier P2/P4b edits
# speedup vs baseline: 1.0103x; 1.0103x over previous
.LBB0_620:
	s_or_b64 exec, exec, s[18:19]
	global_load_dwordx4 v[12:15], v[32:33], off offset:16
	global_load_dwordx4 v[52:55], v[32:33], off
	global_load_dwordx4 v[16:19], v[34:35], off offset:16
	global_load_dwordx4 v[58:61], v[34:35], off
	s_waitcnt vmcnt(4)
	v_lshlrev_b32_e32 v22, 16, v8
	v_and_b32_e32 v23, 0xffff0000, v8
	v_lshlrev_b32_e32 v20, 16, v4
	v_and_b32_e32 v21, 0xffff0000, v4
	v_lshlrev_b32_e32 v66, 16, v0
	v_and_b32_e32 v67, 0xffff0000, v0
	v_lshlrev_b32_e32 v8, 16, v9
	v_and_b32_e32 v9, 0xffff0000, v9
	v_lshlrev_b32_e32 v4, 16, v5
	v_and_b32_e32 v5, 0xffff0000, v5
	s_addk_i32 s29, 0x400
	s_cmpk_eq_i32 s29, 0x800
	s_waitcnt vmcnt(0)
	v_pk_mul_f32 v[22:23], v[58:59], v[22:23]
	s_nop 0
	v_pk_fma_f32 v[52:53], v[52:53], v[20:21], v[22:23]
	global_load_dwordx4 v[20:23], v[36:37], off offset:16
	global_load_dwordx4 v[62:65], v[36:37], off
	v_pk_mul_f32 v[8:9], v[60:61], v[8:9]
	s_waitcnt vmcnt(0)
	v_pk_fma_f32 v[52:53], v[62:63], v[66:67], v[52:53]
	s_nop 0
	v_mul_f32_e32 v0, 0xbfb8aa3b, v52
	v_exp_f32_e32 v0, v0
	v_pk_fma_f32 v[4:5], v[54:55], v[4:5], v[8:9]
	v_lshlrev_b32_e32 v8, 16, v10
	v_and_b32_e32 v9, 0xffff0000, v10
	v_add_f32_e32 v0, 1.0, v0
	v_rcp_f32_e32 v58, v0
	v_mul_f32_e32 v0, 0xbfb8aa3b, v53
	v_exp_f32_e32 v0, v0
	v_pk_mul_f32 v[8:9], v[16:17], v[8:9]
	v_lshlrev_b32_e32 v54, 16, v2
	v_and_b32_e32 v55, 0xffff0000, v2
	v_add_f32_e32 v0, 1.0, v0
	v_rcp_f32_e32 v59, v0
	v_lshlrev_b32_e32 v0, 16, v1
	v_and_b32_e32 v1, 0xffff0000, v1
	v_pk_fma_f32 v[0:1], v[64:65], v[0:1], v[4:5]
	v_pk_mul_f32 v[52:53], v[52:53], v[58:59]
	v_mul_f32_e32 v4, 0xbfb8aa3b, v0
	v_mul_f32_e32 v5, 0xbfb8aa3b, v1
	v_exp_f32_e32 v4, v4
	v_exp_f32_e32 v5, v5
	v_pk_mul_f32 v[52:53], v[52:53], s[68:69] op_sel_hi:[1,0]
	v_add_f32_e32 v4, 1.0, v4
	v_add_f32_e32 v5, 1.0, v5
	v_rcp_f32_e32 v4, v4
	v_rcp_f32_e32 v5, v5
	s_nop 0
	v_pk_mul_f32 v[0:1], v[0:1], v[4:5]
	v_lshlrev_b32_e32 v4, 16, v6
	v_and_b32_e32 v5, 0xffff0000, v6
	v_pk_fma_f32 v[4:5], v[12:13], v[4:5], v[8:9]
	v_lshlrev_b32_e32 v6, 16, v7
	v_pk_fma_f32 v[4:5], v[20:21], v[54:55], v[4:5]
	v_and_b32_e32 v7, 0xffff0000, v7
	v_mul_f32_e32 v2, 0xbfb8aa3b, v4
	v_exp_f32_e32 v2, v2
	v_pk_mul_f32 v[0:1], v[0:1], s[68:69] op_sel_hi:[1,0]
	v_add_f32_e32 v2, 1.0, v2
	v_rcp_f32_e32 v8, v2
	v_mul_f32_e32 v2, 0xbfb8aa3b, v5
	v_exp_f32_e32 v2, v2
	s_nop 0
	v_add_f32_e32 v2, 1.0, v2
	v_rcp_f32_e32 v9, v2
	v_lshlrev_b32_e32 v2, 16, v3
	v_and_b32_e32 v3, 0xffff0000, v3
	v_pk_mul_f32 v[4:5], v[4:5], v[8:9]
	v_lshlrev_b32_e32 v8, 16, v11
	v_and_b32_e32 v9, 0xffff0000, v11
	v_pk_mul_f32 v[8:9], v[18:19], v[8:9]
	v_pk_mul_f32 v[4:5], v[4:5], s[68:69] op_sel_hi:[1,0]
	v_pk_fma_f32 v[6:7], v[14:15], v[6:7], v[8:9]
	v_cvt_pk_bf16_f32 v4, v4, v5
	v_pk_fma_f32 v[2:3], v[22:23], v[2:3], v[6:7]
	s_nop 0
	v_mul_f32_e32 v6, 0xbfb8aa3b, v2
	v_mul_f32_e32 v7, 0xbfb8aa3b, v3
	v_exp_f32_e32 v6, v6
	v_exp_f32_e32 v7, v7
	v_add_f32_e32 v6, 1.0, v6
	v_add_f32_e32 v7, 1.0, v7
	v_rcp_f32_e32 v6, v6
	v_rcp_f32_e32 v7, v7
	s_nop 0
	v_pk_mul_f32 v[2:3], v[2:3], v[6:7]
	s_nop 0
	v_pk_mul_f32 v[6:7], v[2:3], s[68:69] op_sel_hi:[1,0]
	v_cvt_pk_bf16_f32 v3, v0, v1
	v_lshl_add_u64 v[0:1], v[40:41], 0, v[50:51]
	v_cvt_pk_bf16_f32 v2, v52, v53
	v_cvt_pk_bf16_f32 v5, v6, v7
	v_lshl_add_u64 v[0:1], v[0:1], 0, v[174:175]
	global_store_dwordx4 v[0:1], v[2:5], off
	v_mad_u64_u32 v[0:1], s[2:3], v57, s67, v[26:27]
	ds_write2_b32 v0, v2, v3 offset1:1
	ds_write2_b32 v0, v4, v5 offset0:2 offset1:3
	v_mov_b64_e32 v[2:3], v[104:105]
	v_mov_b64_e32 v[4:5], v[106:107]
	v_add_u32_e32 v1, 0x8200, v0
	v_add_u32_e32 v0, 0x8208, v0
	ds_write2_b32 v1, v2, v3 offset1:1
	ds_write2_b32 v0, v4, v5 offset1:1
	s_cbranch_scc1 .LBB0_637

.LBB0_625:
	s_or_b64 exec, exec, s[18:19]
	v_lshl_add_u64 v[88:89], v[46:47], 0, v[48:49]
	global_load_dwordx4 v[76:79], v[88:89], off
	s_and_saveexec_b64 s[18:19], s[2:3]
	s_cbranch_execz .Lp3e_a_1
	global_load_dwordx4 v[80:83], v[88:89], off offset:2048
.Lp3e_a_1:
	s_or_b64 exec, exec, s[18:19]
	v_lshl_add_u64 v[90:91], v[46:47], 0, v[52:53]
	s_and_saveexec_b64 s[18:19], vcc
	s_cbranch_execz .Lp3e_a_2
	global_load_dwordx4 v[72:75], v[90:91], off offset:-2048
.Lp3e_a_2:
	s_or_b64 exec, exec, s[18:19]
	v_lshl_add_u64 v[90:91], v[42:43], 0, v[48:49]
	global_load_dwordx4 v[84:87], v[90:91], off
	v_ashrrev_i32_e32 v12, 5, v174
	v_ashrrev_i32_e32 v13, 31, v12
	v_lshlrev_b64 v[50:51], 13, v[12:13]
	v_lshlrev_b32_e32 v12, 3, v58
	v_and_b32_e32 v59, 0xf8, v12
	global_load_dwordx4 v[12:15], v[24:25], off offset:16
	global_load_dwordx4 v[60:63], v[24:25], off
	global_load_dwordx4 v[16:19], v[28:29], off offset:16
	global_load_dwordx4 v[64:67], v[28:29], off
	s_waitcnt vmcnt(4)
	v_lshlrev_b32_e32 v22, 16, v8
	v_and_b32_e32 v23, 0xffff0000, v8
	v_lshlrev_b32_e32 v20, 16, v4
	v_and_b32_e32 v21, 0xffff0000, v4
	v_lshlrev_b32_e32 v54, 16, v0
	v_and_b32_e32 v55, 0xffff0000, v0
	v_lshlrev_b32_e32 v8, 16, v9
	v_and_b32_e32 v9, 0xffff0000, v9
	v_lshlrev_b32_e32 v4, 16, v5
	v_and_b32_e32 v5, 0xffff0000, v5
	v_lshlrev_b32_e32 v174, 1, v59
	s_waitcnt vmcnt(0)
	v_pk_mul_f32 v[22:23], v[64:65], v[22:23]
	s_nop 0
	v_pk_fma_f32 v[60:61], v[60:61], v[20:21], v[22:23]
	global_load_dwordx4 v[20:23], v[30:31], off offset:16
	global_load_dwordx4 v[68:71], v[30:31], off
	v_pk_mul_f32 v[8:9], v[66:67], v[8:9]
	s_waitcnt vmcnt(0)
	v_pk_fma_f32 v[54:55], v[68:69], v[54:55], v[60:61]
	s_nop 0
	v_mul_f32_e32 v0, 0xbfb8aa3b, v54
	v_exp_f32_e32 v0, v0
	v_pk_fma_f32 v[4:5], v[62:63], v[4:5], v[8:9]
	v_lshlrev_b32_e32 v8, 16, v10
	v_and_b32_e32 v9, 0xffff0000, v10
	v_add_f32_e32 v0, 1.0, v0
	v_rcp_f32_e32 v60, v0
	v_mul_f32_e32 v0, 0xbfb8aa3b, v55
	v_exp_f32_e32 v0, v0
	v_pk_mul_f32 v[8:9], v[16:17], v[8:9]
	v_add_f32_e32 v0, 1.0, v0
	v_rcp_f32_e32 v61, v0
	v_lshlrev_b32_e32 v0, 16, v1
	v_and_b32_e32 v1, 0xffff0000, v1
	v_pk_fma_f32 v[0:1], v[70:71], v[0:1], v[4:5]
	v_pk_mul_f32 v[54:55], v[54:55], v[60:61]
	v_mul_f32_e32 v4, 0xbfb8aa3b, v0
	v_mul_f32_e32 v5, 0xbfb8aa3b, v1
	v_exp_f32_e32 v4, v4
	v_exp_f32_e32 v5, v5
	v_lshlrev_b32_e32 v60, 16, v2
	v_and_b32_e32 v61, 0xffff0000, v2
	v_add_f32_e32 v4, 1.0, v4
	v_add_f32_e32 v5, 1.0, v5
	v_rcp_f32_e32 v4, v4
	v_rcp_f32_e32 v5, v5
	s_nop 0
	v_pk_mul_f32 v[4:5], v[0:1], v[4:5]
	v_lshlrev_b32_e32 v0, 16, v6
	v_and_b32_e32 v1, 0xffff0000, v6
	v_pk_fma_f32 v[0:1], v[12:13], v[0:1], v[8:9]
	v_lshlrev_b32_e32 v6, 16, v11
	v_pk_fma_f32 v[0:1], v[20:21], v[60:61], v[0:1]
	s_nop 0
	v_mul_f32_e32 v2, 0xbfb8aa3b, v0
	v_exp_f32_e32 v2, v2
	s_nop 0
	v_add_f32_e32 v2, 1.0, v2
	v_rcp_f32_e32 v8, v2
	v_mul_f32_e32 v2, 0xbfb8aa3b, v1
	v_exp_f32_e32 v2, v2
	s_nop 0
	v_add_f32_e32 v2, 1.0, v2
	v_rcp_f32_e32 v9, v2
	v_lshlrev_b32_e32 v2, 16, v3
	v_and_b32_e32 v3, 0xffff0000, v3
	v_pk_mul_f32 v[8:9], v[0:1], v[8:9]
	v_lshlrev_b32_e32 v0, 16, v7
	v_and_b32_e32 v1, 0xffff0000, v7
	v_and_b32_e32 v7, 0xffff0000, v11
	v_pk_mul_f32 v[6:7], v[18:19], v[6:7]
	s_nop 0
	v_pk_fma_f32 v[0:1], v[14:15], v[0:1], v[6:7]
	s_nop 0
	v_pk_fma_f32 v[0:1], v[22:23], v[2:3], v[0:1]
	s_nop 0
	v_mul_f32_e32 v2, 0xbfb8aa3b, v0
	v_mul_f32_e32 v3, 0xbfb8aa3b, v1
	v_exp_f32_e32 v2, v2
	v_exp_f32_e32 v3, v3
	v_add_f32_e32 v2, 1.0, v2
	v_add_f32_e32 v3, 1.0, v3
	v_rcp_f32_e32 v2, v2
	v_rcp_f32_e32 v3, v3
	s_nop 0
	v_pk_mul_f32 v[6:7], v[0:1], v[2:3]
	v_cvt_pk_bf16_f32 v1, v4, v5
	v_lshl_add_u64 v[4:5], v[38:39], 0, v[50:51]
	v_cvt_pk_bf16_f32 v0, v54, v55
	v_cvt_pk_bf16_f32 v2, v8, v9
	v_cvt_pk_bf16_f32 v3, v6, v7
	v_lshl_add_u64 v[4:5], v[4:5], 0, v[174:175]
	global_store_dwordx4 v[4:5], v[0:3], off
	v_mov_b32_e32 v4, 0
	v_mov_b32_e32 v5, 0
	v_mov_b32_e32 v0, 0
	v_mov_b32_e32 v6, 0
	v_mov_b32_e32 v7, 0
	s_and_saveexec_b64 s[18:19], vcc
	s_cbranch_execz .LBB0_627
	v_mov_b64_e32 v[4:5], v[72:73]
	v_mov_b64_e32 v[6:7], v[74:75]
.LBB0_627:
	s_or_b64 exec, exec, s[18:19]
	v_mov_b64_e32 v[8:9], v[76:77]
	v_mov_b64_e32 v[10:11], v[78:79]
	v_mov_b32_e32 v1, 0
	v_mov_b32_e32 v2, 0
	v_mov_b32_e32 v3, 0
	s_and_saveexec_b64 s[18:19], s[2:3]
	s_cbranch_execz .LBB0_629
	v_mov_b64_e32 v[0:1], v[80:81]
	v_mov_b64_e32 v[2:3], v[82:83]
.LBB0_629:
	s_or_b64 exec, exec, s[18:19]
	global_load_dwordx4 v[12:15], v[32:33], off offset:16
	global_load_dwordx4 v[52:55], v[32:33], off
	global_load_dwordx4 v[16:19], v[34:35], off offset:16
	global_load_dwordx4 v[60:63], v[34:35], off
	s_waitcnt vmcnt(4)
	v_lshlrev_b32_e32 v22, 16, v8
	v_and_b32_e32 v23, 0xffff0000, v8
	v_lshlrev_b32_e32 v20, 16, v4
	v_and_b32_e32 v21, 0xffff0000, v4
	v_lshlrev_b32_e32 v68, 16, v0
	v_and_b32_e32 v69, 0xffff0000, v0
	v_lshlrev_b32_e32 v8, 16, v9
	v_and_b32_e32 v9, 0xffff0000, v9
	v_lshlrev_b32_e32 v4, 16, v5
	v_and_b32_e32 v5, 0xffff0000, v5
	s_waitcnt vmcnt(0)
	v_pk_mul_f32 v[22:23], v[60:61], v[22:23]
	s_nop 0
	v_pk_fma_f32 v[52:53], v[52:53], v[20:21], v[22:23]
	global_load_dwordx4 v[20:23], v[36:37], off offset:16
	global_load_dwordx4 v[64:67], v[36:37], off
	v_pk_mul_f32 v[8:9], v[62:63], v[8:9]
	s_waitcnt vmcnt(0)
	v_pk_fma_f32 v[52:53], v[64:65], v[68:69], v[52:53]
	s_nop 0
	v_mul_f32_e32 v0, 0xbfb8aa3b, v52
	v_exp_f32_e32 v0, v0
	v_pk_fma_f32 v[4:5], v[54:55], v[4:5], v[8:9]
	v_lshlrev_b32_e32 v8, 16, v10
	v_and_b32_e32 v9, 0xffff0000, v10
	v_add_f32_e32 v0, 1.0, v0
	v_rcp_f32_e32 v60, v0
	v_mul_f32_e32 v0, 0xbfb8aa3b, v53
	v_exp_f32_e32 v0, v0
	v_pk_mul_f32 v[8:9], v[16:17], v[8:9]
	v_lshlrev_b32_e32 v54, 16, v2
	v_and_b32_e32 v55, 0xffff0000, v2
	v_add_f32_e32 v0, 1.0, v0
	v_rcp_f32_e32 v61, v0
	v_lshlrev_b32_e32 v0, 16, v1
	v_and_b32_e32 v1, 0xffff0000, v1
	v_pk_fma_f32 v[0:1], v[66:67], v[0:1], v[4:5]
	v_pk_mul_f32 v[52:53], v[52:53], v[60:61]
	v_mul_f32_e32 v4, 0xbfb8aa3b, v0
	v_mul_f32_e32 v5, 0xbfb8aa3b, v1
	v_exp_f32_e32 v4, v4
	v_exp_f32_e32 v5, v5
	v_pk_mul_f32 v[52:53], v[52:53], s[68:69] op_sel_hi:[1,0]
	v_add_f32_e32 v4, 1.0, v4
	v_add_f32_e32 v5, 1.0, v5
	v_rcp_f32_e32 v4, v4
	v_rcp_f32_e32 v5, v5
	s_nop 0
	v_pk_mul_f32 v[0:1], v[0:1], v[4:5]
	v_lshlrev_b32_e32 v4, 16, v6
	v_and_b32_e32 v5, 0xffff0000, v6
	v_pk_fma_f32 v[4:5], v[12:13], v[4:5], v[8:9]
	v_lshlrev_b32_e32 v6, 16, v7
	v_pk_fma_f32 v[4:5], v[20:21], v[54:55], v[4:5]
	v_and_b32_e32 v7, 0xffff0000, v7
	v_mul_f32_e32 v2, 0xbfb8aa3b, v4
	v_exp_f32_e32 v2, v2
	v_pk_mul_f32 v[0:1], v[0:1], s[68:69] op_sel_hi:[1,0]
	v_add_f32_e32 v2, 1.0, v2
	v_rcp_f32_e32 v8, v2
	v_mul_f32_e32 v2, 0xbfb8aa3b, v5
	v_exp_f32_e32 v2, v2
	s_nop 0
	v_add_f32_e32 v2, 1.0, v2
	v_rcp_f32_e32 v9, v2
	v_lshlrev_b32_e32 v2, 16, v3
	v_and_b32_e32 v3, 0xffff0000, v3
	v_pk_mul_f32 v[4:5], v[4:5], v[8:9]
	v_lshlrev_b32_e32 v8, 16, v11
	v_and_b32_e32 v9, 0xffff0000, v11
	v_pk_mul_f32 v[8:9], v[18:19], v[8:9]
	v_pk_mul_f32 v[4:5], v[4:5], s[68:69] op_sel_hi:[1,0]
	v_pk_fma_f32 v[6:7], v[14:15], v[6:7], v[8:9]
	v_cvt_pk_bf16_f32 v4, v4, v5
	v_pk_fma_f32 v[2:3], v[22:23], v[2:3], v[6:7]
	s_nop 0
	v_mul_f32_e32 v6, 0xbfb8aa3b, v2
	v_mul_f32_e32 v7, 0xbfb8aa3b, v3
	v_exp_f32_e32 v6, v6
	v_exp_f32_e32 v7, v7
	v_add_f32_e32 v6, 1.0, v6
	v_add_f32_e32 v7, 1.0, v7
	v_rcp_f32_e32 v6, v6
	v_rcp_f32_e32 v7, v7
	s_nop 0
	v_pk_mul_f32 v[2:3], v[2:3], v[6:7]
	s_nop 0
	v_pk_mul_f32 v[6:7], v[2:3], s[68:69] op_sel_hi:[1,0]
	v_cvt_pk_bf16_f32 v3, v0, v1
	v_lshl_add_u64 v[0:1], v[40:41], 0, v[50:51]
	v_cvt_pk_bf16_f32 v2, v52, v53
	v_cvt_pk_bf16_f32 v5, v6, v7
	v_lshl_add_u64 v[0:1], v[0:1], 0, v[174:175]
	global_store_dwordx4 v[0:1], v[2:5], off
	v_mad_u64_u32 v[0:1], s[2:3], v58, s67, v[26:27]
	ds_write2_b32 v0, v2, v3 offset1:1
	ds_write2_b32 v0, v4, v5 offset0:2 offset1:3
	v_mov_b64_e32 v[2:3], v[84:85]
	v_mov_b64_e32 v[4:5], v[86:87]
	v_add_u32_e32 v1, 0x8200, v0
	v_add_u32_e32 v0, 0x8208, v0
	v_mov_b32_e32 v6, 0
	v_mov_b32_e32 v7, 0
	ds_write2_b32 v0, v4, v5 offset1:1
	v_add_u32_e32 v0, 0x200, v57
	v_ashrrev_i32_e32 v57, 4, v0
	v_add_u32_e32 v174, s13, v57
	ds_write2_b32 v1, v2, v3 offset1:1
	v_lshl_add_u64 v[2:3], s[16:17], 0, v[174:175]
	v_mov_b32_e32 v0, 0
	v_cmp_lt_i32_e32 vcc, 0, v174
	v_lshlrev_b64 v[52:53], 11, v[2:3]
	v_mov_b32_e32 v4, 0
	v_mov_b32_e32 v5, 0
	s_and_saveexec_b64 s[2:3], vcc
	s_cbranch_execz .LBB0_631
	v_lshl_add_u64 v[2:3], v[44:45], 0, v[52:53]
	global_load_dwordx4 v[4:7], v[2:3], off offset:-2048

.LBB0_633:
	s_or_b64 exec, exec, s[18:19]
	v_lshl_add_u64 v[108:109], v[46:47], 0, v[48:49]
	global_load_dwordx4 v[96:99], v[108:109], off
	s_and_saveexec_b64 s[18:19], s[2:3]
	s_cbranch_execz .Lp3e_b_1
	global_load_dwordx4 v[100:103], v[108:109], off offset:2048
.Lp3e_b_1:
	s_or_b64 exec, exec, s[18:19]
	v_lshl_add_u64 v[110:111], v[46:47], 0, v[52:53]
	s_and_saveexec_b64 s[18:19], vcc
	s_cbranch_execz .Lp3e_b_2
	global_load_dwordx4 v[92:95], v[110:111], off offset:-2048
.Lp3e_b_2:
	s_or_b64 exec, exec, s[18:19]
	v_lshl_add_u64 v[110:111], v[42:43], 0, v[48:49]
	global_load_dwordx4 v[104:107], v[110:111], off
	v_ashrrev_i32_e32 v12, 5, v174
	v_ashrrev_i32_e32 v13, 31, v12
	v_lshlrev_b64 v[50:51], 13, v[12:13]
	v_lshlrev_b32_e32 v12, 3, v57
	v_and_b32_e32 v70, 0xf8, v12
	global_load_dwordx4 v[12:15], v[24:25], off offset:16
	global_load_dwordx4 v[58:61], v[24:25], off
	global_load_dwordx4 v[16:19], v[28:29], off offset:16
	global_load_dwordx4 v[62:65], v[28:29], off
	s_waitcnt vmcnt(4)
	v_lshlrev_b32_e32 v22, 16, v8
	v_and_b32_e32 v23, 0xffff0000, v8
	v_lshlrev_b32_e32 v20, 16, v4
	v_and_b32_e32 v21, 0xffff0000, v4
	v_lshlrev_b32_e32 v54, 16, v0
	v_and_b32_e32 v55, 0xffff0000, v0
	v_lshlrev_b32_e32 v8, 16, v9
	v_and_b32_e32 v9, 0xffff0000, v9
	v_lshlrev_b32_e32 v4, 16, v5
	v_and_b32_e32 v5, 0xffff0000, v5
	v_lshlrev_b32_e32 v174, 1, v70
	s_waitcnt vmcnt(0)
	v_pk_mul_f32 v[22:23], v[62:63], v[22:23]
	s_nop 0
	v_pk_fma_f32 v[58:59], v[58:59], v[20:21], v[22:23]
	global_load_dwordx4 v[20:23], v[30:31], off offset:16
	global_load_dwordx4 v[66:69], v[30:31], off
	v_pk_mul_f32 v[8:9], v[64:65], v[8:9]
	s_waitcnt vmcnt(0)
	v_pk_fma_f32 v[54:55], v[66:67], v[54:55], v[58:59]
	s_nop 0
	v_mul_f32_e32 v0, 0xbfb8aa3b, v54
	v_exp_f32_e32 v0, v0
	v_pk_fma_f32 v[4:5], v[60:61], v[4:5], v[8:9]
	v_lshlrev_b32_e32 v8, 16, v10
	v_and_b32_e32 v9, 0xffff0000, v10
	v_add_f32_e32 v0, 1.0, v0
	v_rcp_f32_e32 v58, v0
	v_mul_f32_e32 v0, 0xbfb8aa3b, v55
	v_exp_f32_e32 v0, v0
	v_pk_mul_f32 v[8:9], v[16:17], v[8:9]
	v_add_f32_e32 v0, 1.0, v0
	v_rcp_f32_e32 v59, v0
	v_lshlrev_b32_e32 v0, 16, v1
	v_and_b32_e32 v1, 0xffff0000, v1
	v_pk_fma_f32 v[0:1], v[68:69], v[0:1], v[4:5]
	v_pk_mul_f32 v[54:55], v[54:55], v[58:59]
	v_mul_f32_e32 v4, 0xbfb8aa3b, v0
	v_mul_f32_e32 v5, 0xbfb8aa3b, v1
	v_exp_f32_e32 v4, v4
	v_exp_f32_e32 v5, v5
	v_lshlrev_b32_e32 v58, 16, v2
	v_and_b32_e32 v59, 0xffff0000, v2
	v_add_f32_e32 v4, 1.0, v4
	v_add_f32_e32 v5, 1.0, v5
	v_rcp_f32_e32 v4, v4
	v_rcp_f32_e32 v5, v5
	s_nop 0
	v_pk_mul_f32 v[4:5], v[0:1], v[4:5]
	v_lshlrev_b32_e32 v0, 16, v6
	v_and_b32_e32 v1, 0xffff0000, v6
	v_pk_fma_f32 v[0:1], v[12:13], v[0:1], v[8:9]
	v_lshlrev_b32_e32 v6, 16, v11
	v_pk_fma_f32 v[0:1], v[20:21], v[58:59], v[0:1]
	s_nop 0
	v_mul_f32_e32 v2, 0xbfb8aa3b, v0
	v_exp_f32_e32 v2, v2
	s_nop 0
	v_add_f32_e32 v2, 1.0, v2
	v_rcp_f32_e32 v8, v2
	v_mul_f32_e32 v2, 0xbfb8aa3b, v1
	v_exp_f32_e32 v2, v2
	s_nop 0
	v_add_f32_e32 v2, 1.0, v2
	v_rcp_f32_e32 v9, v2
	v_lshlrev_b32_e32 v2, 16, v3
	v_and_b32_e32 v3, 0xffff0000, v3
	v_pk_mul_f32 v[8:9], v[0:1], v[8:9]
	v_lshlrev_b32_e32 v0, 16, v7
	v_and_b32_e32 v1, 0xffff0000, v7
	v_and_b32_e32 v7, 0xffff0000, v11
	v_pk_mul_f32 v[6:7], v[18:19], v[6:7]
	s_nop 0
	v_pk_fma_f32 v[0:1], v[14:15], v[0:1], v[6:7]
	s_nop 0
	v_pk_fma_f32 v[0:1], v[22:23], v[2:3], v[0:1]
	s_nop 0
	v_mul_f32_e32 v2, 0xbfb8aa3b, v0
	v_mul_f32_e32 v3, 0xbfb8aa3b, v1
	v_exp_f32_e32 v2, v2
	v_exp_f32_e32 v3, v3
	v_add_f32_e32 v2, 1.0, v2
	v_add_f32_e32 v3, 1.0, v3
	v_rcp_f32_e32 v2, v2
	v_rcp_f32_e32 v3, v3
	s_nop 0
	v_pk_mul_f32 v[6:7], v[0:1], v[2:3]
	v_cvt_pk_bf16_f32 v1, v4, v5
	v_lshl_add_u64 v[4:5], v[38:39], 0, v[50:51]
	v_cvt_pk_bf16_f32 v0, v54, v55
	v_cvt_pk_bf16_f32 v2, v8, v9
	v_cvt_pk_bf16_f32 v3, v6, v7
	v_lshl_add_u64 v[4:5], v[4:5], 0, v[174:175]
	global_store_dwordx4 v[4:5], v[0:3], off
	v_mov_b32_e32 v4, 0
	v_mov_b32_e32 v5, 0
	v_mov_b32_e32 v0, 0
	v_mov_b32_e32 v6, 0
	v_mov_b32_e32 v7, 0
	s_and_saveexec_b64 s[18:19], vcc
	s_cbranch_execz .LBB0_635
	v_mov_b64_e32 v[4:5], v[92:93]
	v_mov_b64_e32 v[6:7], v[94:95]
.LBB0_635:
	s_or_b64 exec, exec, s[18:19]
	v_mov_b64_e32 v[8:9], v[96:97]
	v_mov_b64_e32 v[10:11], v[98:99]
	v_mov_b32_e32 v1, 0
	v_mov_b32_e32 v2, 0
	v_mov_b32_e32 v3, 0
	s_and_saveexec_b64 s[18:19], s[2:3]
	s_cbranch_execz .LBB0_620
	v_mov_b64_e32 v[0:1], v[100:101]
	v_mov_b64_e32 v[2:3], v[102:103]
	s_branch .LBB0_620

.LBB0_788:
	s_and_b32 s98, s37, 0xffffffe0
	s_and_b32 s99, s37, 7
	s_lshl_b32 s99, s99, 2
	s_or_b32 s98, s98, s99
	s_bfe_u32 s99, s37, 0x20003
	s_or_b32 s98, s98, s99
	s_ashr_i32 s1, s98, 2
	s_bfe_u32 s0, s98, 0x30002
	s_and_b32 s1, s1, -8
	s_or_b32 s2, s1, s0
	s_bfe_u32 s74, s98, 0x10001
	s_lshl_b32 s0, s2, 1
	v_mov_b32_e32 v1, v172
	s_or_b32 s0, s0, s74
	s_ashr_i32 s1, s0, 31
	v_readfirstlane_b32 s16, v1
	v_readlane_b32 s3, v254, 11
	s_ashr_i32 s53, s16, 6
	s_and_b32 s17, s98, 1
	s_lshl_b64 s[12:13], s[0:1], s3
	s_bfe_i32 s14, s98, 0x10001
	s_ashr_i32 s19, s16, 8
	s_and_b32 s18, s53, 3
	s_lshl_b32 s3, s17, 13
	s_lshl_b64 s[8:9], s[12:13], 2
	s_add_u32 s38, s26, s8
	v_readlane_b32 s4, v254, 25
	s_addc_u32 s39, s27, s9
	s_lshl_b64 s[4:5], s[0:1], s4
	s_lshl_b32 s0, s19, 12
	s_add_i32 s10, s0, s3
	s_lshl_b64 s[6:7], s[4:5], 15
	s_ashr_i32 s11, s10, 31
	s_lshl_b64 s[0:1], s[4:5], 8
	s_add_u32 s0, s28, s0
	s_addc_u32 s1, s29, s1
	s_lshl_b32 s3, s18, 6
	s_add_u32 s0, s0, s3
	s_addc_u32 s1, s1, 0
	s_ashr_i32 s3, s2, 31
	v_readlane_b32 s15, v254, 27
	s_lshl_b64 s[2:3], s[2:3], s15
	s_lshl_b32 s40, s18, 13
	s_lshl_b64 s[2:3], s[2:3], 1
	s_add_u32 s41, s20, s2
	s_addc_u32 s42, s21, s3
	s_add_u32 s2, s22, s2
	s_addc_u32 s3, s23, s3
	s_lshl_b32 s15, s17, 14
	s_add_u32 s43, s2, s15
	s_addc_u32 s44, s3, 0
	s_add_u32 s6, s33, s6
	s_addc_u32 s7, s34, s7
	s_lshl_b64 s[2:3], s[10:11], 1
	s_add_u32 s2, s6, s2
	s_addc_u32 s3, s7, s3
	s_lshl_b32 s6, s18, 11
	s_add_u32 s10, s2, s6
	s_addc_u32 s11, s3, 0
	s_lshl_b64 s[2:3], s[4:5], 2
	s_add_u32 s45, s30, s2
	v_readlane_b32 s56, v253, 3
	s_addc_u32 s46, s31, s3
	s_and_b32 s14, s14, s92
	s_mov_b32 s15, s56
	s_lshl_b64 s[2:3], s[14:15], 15
	v_readlane_b32 s60, v253, 7
	s_add_u32 s15, s41, s2
	v_readlane_b32 s61, v253, 8
	s_addc_u32 s60, s42, s3
	s_add_u32 s61, s43, s2
	s_addc_u32 s72, s44, s3
	s_cmp_lt_i32 s53, 6
	s_mul_i32 s47, s53, 0x1800
	s_cselect_b64 s[2:3], -1, 0
	s_add_i32 s48, s47, 0xffff8000
	s_add_u32 s7, s61, s48
	s_addc_u32 s50, s72, 0
	s_ashr_i32 s49, s47, 31
	v_readlane_b32 s57, v253, 4
	s_add_u32 s56, s15, s47
	s_addc_u32 s57, s60, s49
	v_readlane_b32 s62, v253, 9
	v_readlane_b32 s63, v253, 10
	s_mul_i32 s6, s53, 6
	s_and_b64 s[4:5], s[2:3], exec
	s_cselect_b32 s62, s56, s7
	s_cselect_b32 s63, s57, s50
	s_add_i32 s75, s47, 0
	s_or_b32 s6, s6, 1
	s_cmp_lt_i32 s6, 32
	s_cselect_b64 s[4:5], -1, 0
	s_lshl_b32 s50, s6, 10
	s_ashr_i32 s51, s50, 31
	s_add_u32 s54, s15, s50
	v_readlane_b32 s58, v253, 5
	s_addc_u32 s55, s60, s51
	s_add_i32 s52, s50, 0xffff8000
	v_readlane_b32 s59, v253, 6
	s_add_u32 s58, s61, s52
	s_addc_u32 s59, s72, 0
	v_readlane_b32 s64, v253, 11
	v_readlane_b32 s65, v253, 12
	s_and_b64 s[6:7], s[4:5], exec
	s_cselect_b32 s64, s54, s58
	s_cselect_b32 s65, s55, s59
	s_add_i32 s76, s50, 0
	s_cmp_lt_i32 s53, 5
	s_cselect_b64 s[6:7], -1, 0
	s_add_u32 s58, s56, 0x800
	v_readlane_b32 s66, v253, 13
	s_addc_u32 s59, s57, 0
	s_add_i32 s53, s47, 0xffff8800
	v_readlane_b32 s67, v253, 14
	s_add_u32 s66, s61, s53
	s_addc_u32 s67, s72, 0
	s_and_b64 s[54:55], s[6:7], exec
	s_cselect_b32 s66, s58, s66
	s_cselect_b32 s67, s59, s67
	s_add_i32 s77, s75, 0x800
	s_add_u32 s55, s56, 0xc00
	s_addc_u32 s58, s57, 0
	s_add_i32 s54, s47, 0xffff8c00
	v_readlane_b32 s69, v253, 16
	s_add_u32 s59, s61, s54
	s_addc_u32 s69, s72, 0
	v_readlane_b32 s68, v253, 15
	s_and_b64 s[56:57], s[6:7], exec
	s_cselect_b32 s68, s55, s59
	s_cselect_b32 s69, s58, s69
	s_add_i32 s55, s47, 0x1000
	v_readlane_b32 s70, v253, 17
	s_add_i32 s78, s75, 0xc00
	s_ashr_i32 s56, s55, 31
	v_readlane_b32 s71, v253, 18
	s_add_u32 s70, s15, s55
	s_addc_u32 s71, s60, s56
	s_add_i32 s57, s47, 0xffff9000
	s_add_u32 s73, s61, s57
	s_addc_u32 s79, s72, 0
	s_and_b64 s[58:59], s[6:7], exec
	s_cselect_b32 s70, s70, s73
	s_cselect_b32 s71, s71, s79
	s_add_i32 s58, s47, 0x1400
	s_add_i32 s79, s75, 0x1000
	s_ashr_i32 s59, s58, 31
	s_add_u32 s15, s15, s58
	s_addc_u32 s80, s60, s59
	s_add_i32 s60, s47, 0xffff9400
	s_add_u32 s61, s61, s60
	s_addc_u32 s81, s72, 0
	s_and_b64 s[72:73], s[6:7], exec
	s_cselect_b32 s72, s15, s61
	s_cselect_b32 s73, s80, s81
	v_and_b32_e32 v6, 63, v1
	s_mov_b32 m0, s75
	s_addk_i32 s75, 0x1400
	v_lshlrev_b32_e32 v174, 4, v6
	s_add_u32 s61, s24, s8
	global_load_lds_dwordx4 v174, s[62:63]
	s_addc_u32 s62, s25, s9
	s_cmp_eq_u32 s74, 0
	s_mov_b32 m0, s76
	s_cselect_b64 s[8:9], -1, 0
	global_load_lds_dwordx4 v174, s[64:65]
	s_mov_b32 m0, s77
	s_and_b64 s[64:65], s[8:9], exec
	global_load_lds_dwordx4 v174, s[66:67]
	s_mov_b32 m0, s78
	s_cselect_b32 s63, 0x7f, 0
	s_lshl_b32 s64, s19, 13
	s_lshl_b64 s[12:13], s[12:13], 1
	global_load_lds_dwordx4 v174, s[68:69]
	s_mov_b32 m0, s79
	s_add_u32 s12, s35, s12
	global_load_lds_dwordx4 v174, s[70:71]
	s_mov_b32 m0, s75
	s_addc_u32 s13, s36, s13
	s_lshl_b32 s19, s14, 7
	s_lshl_b32 s14, s14, 8
	v_bfe_u32 v7, v1, 5, 1
	global_load_lds_dwordx4 v174, s[72:73]
	s_add_u32 s14, s12, s14
	v_readlane_b32 s68, v253, 3
	s_addc_u32 s15, s13, 0
	v_lshlrev_b32_e32 v0, 4, v7
	s_or_b32 s66, s19, s63
	s_mov_b32 s67, s68
	global_load_dwordx4 v[32:35], v0, s[14:15] offset:32
	global_load_dwordx4 v[36:39], v0, s[14:15] offset:64
	global_load_dwordx4 v[40:43], v0, s[14:15] offset:96
	global_load_dwordx4 v[44:47], v0, s[14:15] offset:128
	global_load_dwordx4 v[48:51], v0, s[14:15] offset:160
	global_load_dwordx4 v[52:55], v0, s[14:15] offset:192
	global_load_dwordx4 v[56:59], v0, s[14:15] offset:224
	s_lshl_b64 s[66:67], s[66:67], 2
	v_readlane_b32 s69, v253, 4
	s_add_u32 s68, s38, s66
	s_addc_u32 s69, s39, s67
	s_add_u32 s66, s61, s66
	s_addc_u32 s67, s62, s67
	global_load_dwordx4 v[60:63], v0, s[14:15]
	global_load_dword v110, v175, s[68:69]
	global_load_dword v112, v175, s[66:67]
	v_and_b32_e32 v8, 31, v1
	v_mov_b32_e32 v1, v175
	v_lshlrev_b32_e32 v68, 4, v8
	v_mov_b32_e32 v69, v175
	v_lshl_add_u64 v[74:75], s[12:13], 0, v[0:1]
	s_cmpk_lt_u32 s16, 0x100
	v_or_b32_e32 v0, s17, v8
	v_lshl_add_u64 v[2:3], s[10:11], 0, v[68:69]
	s_cselect_b64 s[10:11], -1, 0
	v_cmp_eq_u32_e32 vcc, 0, v0
	s_and_b64 s[12:13], vcc, s[10:11]
	v_lshlrev_b32_e32 v4, 3, v7
	v_mov_b32_e32 v5, v175
	s_cmp_eq_u32 s18, 0
	v_lshl_add_u64 v[72:73], s[0:1], 0, v[4:5]
	s_cselect_b64 s[0:1], -1, 0
	v_cmp_gt_u32_e32 vcc, 32, v6
	v_mov_b32_e32 v76, 0
	s_mov_b32 s67, 0
	v_lshl_add_u64 v[70:71], v[2:3], 0, v[4:5]
	v_lshlrev_b32_e32 v69, 9, v7
	s_and_b64 s[14:15], s[0:1], vcc
	v_mov_b32_e32 v111, 0xf149f2ca
	s_mov_b32 s65, s92
	v_mov_b32_e32 v77, v76
	v_mov_b32_e32 v78, v76
	v_mov_b32_e32 v79, v76
	v_mov_b32_e32 v80, v76
	v_mov_b32_e32 v81, v76
	v_mov_b32_e32 v82, v76
	v_mov_b32_e32 v83, v76
	v_mov_b32_e32 v84, v76
	v_mov_b32_e32 v85, v76
	v_mov_b32_e32 v86, v76
	v_mov_b32_e32 v87, v76
	v_mov_b32_e32 v88, v76
	v_mov_b32_e32 v89, v76
	v_mov_b32_e32 v90, v76
	v_mov_b32_e32 v91, v76
	v_mov_b32_e32 v92, v76
	v_mov_b32_e32 v93, v76
	v_mov_b32_e32 v94, v76
	v_mov_b32_e32 v95, v76
	v_mov_b32_e32 v96, v76
	v_mov_b32_e32 v97, v76
	v_mov_b32_e32 v98, v76
	v_mov_b32_e32 v99, v76
	v_mov_b32_e32 v100, v76
	v_mov_b32_e32 v101, v76
	v_mov_b32_e32 v102, v76
	v_mov_b32_e32 v103, v76
	v_mov_b32_e32 v104, v76
	v_mov_b32_e32 v105, v76
	v_mov_b32_e32 v106, v76
	v_mov_b32_e32 v107, v76
	v_readlane_b32 s0, v254, 8
	v_readlane_b32 s70, v253, 5
	v_readlane_b32 s71, v253, 6
	v_readlane_b32 s72, v253, 7
	v_readlane_b32 s73, v253, 8
	v_readlane_b32 s74, v253, 9
	v_readlane_b32 s75, v253, 10
	v_readlane_b32 s76, v253, 11
	v_readlane_b32 s77, v253, 12
	v_readlane_b32 s78, v253, 13
	v_readlane_b32 s79, v253, 14
	v_readlane_b32 s80, v253, 15
	v_readlane_b32 s81, v253, 16
	v_readlane_b32 s82, v253, 17
	v_readlane_b32 s83, v253, 18
	s_branch .LBB0_790

	.amdhsa_kernel _Z14fwd_megakernel4Args
		.amdhsa_group_segment_fixed_size 0
		.amdhsa_private_segment_fixed_size 0
		.amdhsa_kernarg_size 376
		.amdhsa_user_sgpr_count 2
		.amdhsa_user_sgpr_dispatch_ptr 0
		.amdhsa_user_sgpr_queue_ptr 0
		.amdhsa_user_sgpr_kernarg_segment_ptr 1
		.amdhsa_user_sgpr_dispatch_id 0
		.amdhsa_user_sgpr_kernarg_preload_length 0
		.amdhsa_user_sgpr_kernarg_preload_offset 0
		.amdhsa_user_sgpr_private_segment_size 0
		.amdhsa_uses_dynamic_stack 0
		.amdhsa_enable_private_segment 0
		.amdhsa_system_sgpr_workgroup_id_x 1
		.amdhsa_system_sgpr_workgroup_id_y 0
		.amdhsa_system_sgpr_workgroup_id_z 0
		.amdhsa_system_sgpr_workgroup_info 0
		.amdhsa_system_vgpr_workitem_id 2
		.amdhsa_next_free_vgpr 255
		.amdhsa_next_free_sgpr 102
		.amdhsa_accum_offset 256
		.amdhsa_reserve_vcc 1
		.amdhsa_float_round_mode_32 0
		.amdhsa_float_round_mode_16_64 0
		.amdhsa_float_denorm_mode_32 3
		.amdhsa_float_denorm_mode_16_64 3
		.amdhsa_dx10_clamp 1
		.amdhsa_ieee_mode 1
		.amdhsa_fp16_overflow 0
		.amdhsa_tg_split 0
		.amdhsa_exception_fp_ieee_invalid_op 0
		.amdhsa_exception_fp_denorm_src 0
		.amdhsa_exception_fp_ieee_div_zero 0
		.amdhsa_exception_fp_ieee_overflow 0
		.amdhsa_exception_fp_ieee_underflow 0
		.amdhsa_exception_fp_ieee_inexact 0
		.amdhsa_exception_int_div_zero 0
	.end_amdhsa_kernel

amdhsa.kernels:
  - .agpr_count:     0
    .args:
      - .offset:         0
        .size:           120
        .value_kind:     by_value
      - .offset:         120
        .size:           4
        .value_kind:     hidden_block_count_x
      - .offset:         124
        .size:           4
        .value_kind:     hidden_block_count_y
      - .offset:         128
        .size:           4
        .value_kind:     hidden_block_count_z
      - .offset:         132
        .size:           2
        .value_kind:     hidden_group_size_x
      - .offset:         134
        .size:           2
        .value_kind:     hidden_group_size_y
      - .offset:         136
        .size:           2
        .value_kind:     hidden_group_size_z
      - .offset:         138
        .size:           2
        .value_kind:     hidden_remainder_x
      - .offset:         140
        .size:           2
        .value_kind:     hidden_remainder_y
      - .offset:         142
        .size:           2
        .value_kind:     hidden_remainder_z
      - .offset:         160
        .size:           8
        .value_kind:     hidden_global_offset_x
      - .offset:         168
        .size:           8
        .value_kind:     hidden_global_offset_y
      - .offset:         176
        .size:           8
        .value_kind:     hidden_global_offset_z
      - .offset:         184
        .size:           2
        .value_kind:     hidden_grid_dims
      - .offset:         208
        .size:           8
        .value_kind:     hidden_multigrid_sync_arg
      - .offset:         240
        .size:           4
        .value_kind:     hidden_dynamic_lds_size
    .group_segment_fixed_size: 0
    .kernarg_segment_align: 8
    .kernarg_segment_size: 376
    .language:       OpenCL C
    .language_version:
      - 2
      - 0
    .max_flat_workgroup_size: 512
    .name:           _Z14fwd_megakernel4Args
    .private_segment_fixed_size: 0
    .sgpr_count:     108
    .sgpr_spill_count: 172
    .symbol:         _Z14fwd_megakernel4Args.kd
    .uniform_work_group_size: 1
    .uses_dynamic_stack: false
    .vgpr_count:     255
    .vgpr_spill_count: 0
    .wavefront_size: 64
